# in-proj GEMM steady K-loop rescheduled: fragment reads first after barrier, SGPR-base global loads, ds_writes interleaved per MFMA group, 4-deep A-fragment ring
# speedup vs baseline: 1.2323x; 1.2323x over previous
; template <int EPI>
; DI void gemm_phase(const P& p, int l, const u16* __restrict__ A, const u16* __restrict__ Bt, int mpx, char* lds) {
;     ...
;   while (true) {
;   const int tn = t + 1;
;   int m1 = 0, n1 = 0;
;   const bool has_next = tile_coords<EPI>(tn, mpx, m1, n1);
;   const u16* Agn = A + (size_t)m1 * 1024;
;   const u16* Bgn = Bt + (size_t)n1 * 1024;
;   f32x4 acc[8][4];
; #pragma unroll
;   for (int i = 0; i < 8; ++i)
; #pragma unroll
;     for (int j = 0; j < 4; ++j) acc[i][j] = zero4();
;   {
;   const int lane = tid & 63, w = tid >> 6, r = lane & 15, g = lane >> 4, wm = w >> 2, wn = w & 3;
;   __syncthreads();
;   GLOAD(Ag, Bg, 64)
;   __builtin_amdgcn_sched_barrier(0);
;   GCOMPUTE_KS(As0, Bs0, 0)
;   __builtin_amdgcn_sched_barrier(0);
;   GSTORE(As1, Bs1)
;   GLOAD(Ag, Bg, 128)
;   __builtin_amdgcn_sched_barrier(0);
;   GCOMPUTE_KS(As0, Bs0, 1)
.LBB0_81:
	v_lshl_add_u64 v[138:139], s[40:41], 0, v[196:197]
	v_add_co_u32_e32 v140, vcc, s33, v138
	v_lshl_add_u64 v[146:147], s[0:1], 0, v[196:197]
	s_nop 0
	v_addc_co_u32_e32 v141, vcc, 0, v139, vcc
	v_add_co_u32_e32 v142, vcc, s35, v138
	s_waitcnt lgkmcnt(0)
	s_nop 0
	v_addc_co_u32_e32 v143, vcc, 0, v139, vcc
	v_add_co_u32_e32 v144, vcc, s39, v138
	s_barrier
	s_nop 0
	v_addc_co_u32_e32 v145, vcc, 0, v139, vcc
	v_add_co_u32_e32 v150, vcc, s33, v146
	s_nop 1
	v_addc_co_u32_e32 v151, vcc, 0, v147, vcc
	v_add_co_u32_e32 v154, vcc, s35, v146
	global_load_dwordx4 v[2:5], v[138:139], off offset:128
	global_load_dwordx4 v[6:9], v[140:141], off offset:128
	v_addc_co_u32_e32 v155, vcc, 0, v147, vcc
	v_add_co_u32_e32 v158, vcc, s39, v146
	global_load_dwordx4 v[10:13], v[142:143], off offset:128
	global_load_dwordx4 v[14:17], v[144:145], off offset:128
	global_load_dwordx4 v[18:21], v[146:147], off offset:128
	global_load_dwordx4 v[22:25], v[150:151], off offset:128
	v_addc_co_u32_e32 v159, vcc, 0, v147, vcc
	global_load_dwordx4 v[26:29], v[154:155], off offset:128
	global_load_dwordx4 v[30:33], v[158:159], off offset:128
	s_mov_b32 s57, s3
	s_lshl_b64 s[42:43], s[56:57], 11
	s_lshl_b32 s2, s51, 11
	s_add_u32 s58, s16, s42
	s_addc_u32 s59, s17, s43
	ds_read_b128 v[34:37], v205
	ds_read_b128 v[38:41], v204 offset:32768
	ds_read_b128 v[42:45], v204 offset:34816
	ds_read_b128 v[46:49], v205 offset:2048
	ds_read_b128 v[58:61], v204 offset:36864
	ds_read_b128 v[62:65], v204 offset:38912
	ds_read_b128 v[82:85], v205 offset:4096
	ds_read_b128 v[86:89], v205 offset:6144
	ds_read_b128 v[114:117], v205 offset:8192
	ds_read_b128 v[118:121], v205 offset:10240
	s_waitcnt vmcnt(25)
	ds_read_b128 v[130:133], v205 offset:12288
	s_waitcnt vmcnt(24)
	ds_read_b128 v[134:137], v205 offset:14336
	s_waitcnt lgkmcnt(10)
	v_mfma_f32_16x16x32_bf16 v[50:53], v[34:37], v[38:41], 0
	s_add_u32 s60, s24, s2
	s_addc_u32 s61, s25, 0
	s_waitcnt lgkmcnt(9)
	v_mfma_f32_16x16x32_bf16 v[54:57], v[34:37], v[42:45], 0
	s_waitcnt lgkmcnt(7)
	v_mfma_f32_16x16x32_bf16 v[66:69], v[34:37], v[58:61], 0
	s_waitcnt lgkmcnt(6)
	v_mfma_f32_16x16x32_bf16 v[34:37], v[34:37], v[62:65], 0
	v_mfma_f32_16x16x32_bf16 v[70:73], v[46:49], v[38:41], 0
	v_mfma_f32_16x16x32_bf16 v[74:77], v[46:49], v[42:45], 0
	v_mfma_f32_16x16x32_bf16 v[78:81], v[46:49], v[58:61], 0
	v_mfma_f32_16x16x32_bf16 v[46:49], v[46:49], v[62:65], 0
	s_waitcnt lgkmcnt(5)
	v_mfma_f32_16x16x32_bf16 v[90:93], v[82:85], v[38:41], 0
	v_mfma_f32_16x16x32_bf16 v[94:97], v[82:85], v[42:45], 0
	v_mfma_f32_16x16x32_bf16 v[98:101], v[82:85], v[58:61], 0
	v_mfma_f32_16x16x32_bf16 v[82:85], v[82:85], v[62:65], 0
	s_waitcnt lgkmcnt(4)
	v_mfma_f32_16x16x32_bf16 v[102:105], v[86:89], v[38:41], 0
	v_mfma_f32_16x16x32_bf16 v[106:109], v[86:89], v[42:45], 0
	v_mfma_f32_16x16x32_bf16 v[110:113], v[86:89], v[58:61], 0
	v_mfma_f32_16x16x32_bf16 v[86:89], v[86:89], v[62:65], 0
	s_waitcnt lgkmcnt(3)
	v_mfma_f32_16x16x32_bf16 v[122:125], v[114:117], v[38:41], 0
	v_mfma_f32_16x16x32_bf16 v[126:129], v[114:117], v[42:45], 0
	v_mfma_f32_16x16x32_bf16 v[162:165], v[114:117], v[58:61], 0
	v_mfma_f32_16x16x32_bf16 v[114:117], v[114:117], v[62:65], 0
	s_waitcnt lgkmcnt(2)
	v_mfma_f32_16x16x32_bf16 v[166:169], v[118:121], v[38:41], 0
	v_mfma_f32_16x16x32_bf16 v[170:173], v[118:121], v[42:45], 0
	v_mfma_f32_16x16x32_bf16 v[174:177], v[118:121], v[58:61], 0
	v_mfma_f32_16x16x32_bf16 v[118:121], v[118:121], v[62:65], 0
	s_waitcnt lgkmcnt(1)
	v_mfma_f32_16x16x32_bf16 v[178:181], v[130:133], v[38:41], 0
	v_mfma_f32_16x16x32_bf16 v[182:185], v[130:133], v[42:45], 0
	v_mfma_f32_16x16x32_bf16 v[186:189], v[130:133], v[58:61], 0
	v_mfma_f32_16x16x32_bf16 v[190:193], v[130:133], v[62:65], 0
	s_waitcnt lgkmcnt(0)
	v_mfma_f32_16x16x32_bf16 v[234:237], v[134:137], v[38:41], 0
	v_mfma_f32_16x16x32_bf16 v[238:241], v[134:137], v[42:45], 0
	v_mfma_f32_16x16x32_bf16 v[242:245], v[134:137], v[58:61], 0
	v_mfma_f32_16x16x32_bf16 v[246:249], v[134:137], v[62:65], 0
	s_waitcnt vmcnt(7)
	ds_write_b128 v202, v[2:5]
	s_waitcnt vmcnt(6)
	ds_write_b128 v227, v[6:9]
	s_waitcnt vmcnt(5)
	ds_write_b128 v228, v[10:13]
	s_waitcnt vmcnt(4)
	ds_write_b128 v229, v[14:17]
	s_waitcnt vmcnt(3)
	ds_write_b128 v203, v[18:21]
	s_waitcnt vmcnt(2)
	ds_write_b128 v230, v[22:25]
	s_waitcnt vmcnt(1)
	ds_write_b128 v231, v[26:29]
	s_waitcnt vmcnt(0)
	ds_write_b128 v232, v[30:33]
	global_load_dwordx4 v[130:133], v[138:139], off offset:256
	global_load_dwordx4 v[134:137], v[140:141], off offset:256
	s_nop 0
	global_load_dwordx4 v[138:141], v[142:143], off offset:256
	s_nop 0
	global_load_dwordx4 v[142:145], v[144:145], off offset:256
	s_nop 0
	global_load_dwordx4 v[146:149], v[146:147], off offset:256
	s_nop 0
	global_load_dwordx4 v[150:153], v[150:151], off offset:256
	s_nop 0
	global_load_dwordx4 v[154:157], v[154:155], off offset:256
	s_nop 0
	global_load_dwordx4 v[158:161], v[158:159], off offset:256
	ds_read_b128 v[2:5], v207
	ds_read_b128 v[250:253], v206 offset:32768
	ds_read_b128 v[216:219], v206 offset:34816
	ds_read_b128 v[212:215], v206 offset:36864
	ds_read_b128 v[220:223], v206 offset:38912
	s_waitcnt lgkmcnt(3)
	v_mfma_f32_16x16x32_bf16 v[6:9], v[2:5], v[250:253], v[50:53]
	s_waitcnt lgkmcnt(2)
	v_mfma_f32_16x16x32_bf16 v[10:13], v[2:5], v[216:219], v[54:57]
	s_waitcnt lgkmcnt(1)
	v_mfma_f32_16x16x32_bf16 v[14:17], v[2:5], v[212:215], v[66:69]
	s_waitcnt lgkmcnt(0)
	v_mfma_f32_16x16x32_bf16 v[18:21], v[2:5], v[220:223], v[34:37]
	ds_read_b128 v[2:5], v207 offset:2048
	s_waitcnt lgkmcnt(0)
; #define GCOMPUTE(AS, BS) GCOMPUTE_KS(AS, BS, 0) GCOMPUTE_KS(AS, BS, 1)
; template <int EPI>
; DI void gemm_phase(const P& p, int l, const u16* __restrict__ A, const u16* __restrict__ Bt, int mpx, char* lds) {
;     ...
;   GCOMPUTE_KS(As0, Bs0, 1)
;   __builtin_amdgcn_sched_barrier(0);
; #pragma unroll 1
;   for (int kk = 1; kk < 15; kk += 2) {
;     __syncthreads();
;     GSTORE(As0, Bs0)
;     GLOAD(Ag, Bg, (kk + 2) * 64)
;     __builtin_amdgcn_sched_barrier(0);
;     GCOMPUTE(As1, Bs1)
;     __builtin_amdgcn_sched_barrier(0);
;     __syncthreads();
;     GSTORE(As1, Bs1)
;     {
;       const bool in_tile = kk + 3 < 16;
;       const u16* pa = in_tile ? Ag : Agn;
;       const u16* pb = in_tile ? Bg : Bgn;
;       const int k0 = in_tile ? (kk + 3) * 64 : 0;
;       GLOAD(pa, pb, k0)
;     }
;     __builtin_amdgcn_sched_barrier(0);
;     GCOMPUTE(As0, Bs0)
	v_mfma_f32_16x16x32_bf16 v[22:25], v[2:5], v[250:253], v[70:73]
	v_mfma_f32_16x16x32_bf16 v[26:29], v[2:5], v[216:219], v[74:77]
	v_mfma_f32_16x16x32_bf16 v[30:33], v[2:5], v[212:215], v[78:81]
	v_mfma_f32_16x16x32_bf16 v[34:37], v[2:5], v[220:223], v[46:49]
	ds_read_b128 v[2:5], v207 offset:4096
	s_waitcnt lgkmcnt(0)
	v_mfma_f32_16x16x32_bf16 v[38:41], v[2:5], v[250:253], v[90:93]
	v_mfma_f32_16x16x32_bf16 v[42:45], v[2:5], v[216:219], v[94:97]
	v_mfma_f32_16x16x32_bf16 v[46:49], v[2:5], v[212:215], v[98:101]
	v_mfma_f32_16x16x32_bf16 v[50:53], v[2:5], v[220:223], v[82:85]
	ds_read_b128 v[2:5], v207 offset:6144
	s_waitcnt lgkmcnt(0)
	v_mfma_f32_16x16x32_bf16 v[54:57], v[2:5], v[250:253], v[102:105]
	v_mfma_f32_16x16x32_bf16 v[58:61], v[2:5], v[216:219], v[106:109]
	v_mfma_f32_16x16x32_bf16 v[62:65], v[2:5], v[212:215], v[110:113]
	v_mfma_f32_16x16x32_bf16 v[66:69], v[2:5], v[220:223], v[86:89]
	ds_read_b128 v[2:5], v207 offset:8192
	s_waitcnt lgkmcnt(0)
	v_mfma_f32_16x16x32_bf16 v[70:73], v[2:5], v[250:253], v[122:125]
	v_mfma_f32_16x16x32_bf16 v[74:77], v[2:5], v[216:219], v[126:129]
	v_mfma_f32_16x16x32_bf16 v[78:81], v[2:5], v[212:215], v[162:165]
	v_mfma_f32_16x16x32_bf16 v[82:85], v[2:5], v[220:223], v[114:117]
	ds_read_b128 v[2:5], v207 offset:10240
	s_waitcnt lgkmcnt(0)
	v_mfma_f32_16x16x32_bf16 v[86:89], v[2:5], v[250:253], v[166:169]
	v_mfma_f32_16x16x32_bf16 v[90:93], v[2:5], v[216:219], v[170:173]
	v_mfma_f32_16x16x32_bf16 v[94:97], v[2:5], v[212:215], v[174:177]
	v_mfma_f32_16x16x32_bf16 v[98:101], v[2:5], v[220:223], v[118:121]
	ds_read_b128 v[2:5], v207 offset:12288
	s_waitcnt lgkmcnt(0)
	v_mfma_f32_16x16x32_bf16 v[102:105], v[2:5], v[250:253], v[178:181]
	v_mfma_f32_16x16x32_bf16 v[106:109], v[2:5], v[216:219], v[182:185]
	v_mfma_f32_16x16x32_bf16 v[110:113], v[2:5], v[212:215], v[186:189]
	v_mfma_f32_16x16x32_bf16 v[114:117], v[2:5], v[220:223], v[190:193]
	ds_read_b128 v[2:5], v207 offset:14336
	s_waitcnt lgkmcnt(0)
	v_mfma_f32_16x16x32_bf16 v[118:121], v[2:5], v[250:253], v[234:237]
	v_mfma_f32_16x16x32_bf16 v[122:125], v[2:5], v[216:219], v[238:241]
	v_mfma_f32_16x16x32_bf16 v[126:129], v[2:5], v[212:215], v[242:245]
	v_mfma_f32_16x16x32_bf16 v[2:5], v[2:5], v[220:223], v[246:249]
	s_mov_b32 s49, 1
	s_movk_i32 s47, 0x100
	s_mov_b64 s[42:43], s[0:1]
	s_mov_b64 s[44:45], s[40:41]
	v_add_u32_e32 v208, s33, v196
	v_add_u32_e32 v209, s35, v196
	v_add_u32_e32 v210, s39, v196
.LBB0_82:
	s_add_i32 s48, s49, 2
	s_barrier
	ds_read_b128 v[212:215], v198
	ds_read_b128 v[216:219], v198 offset:2048
	ds_read_b128 v[220:223], v198 offset:4096
	ds_read_b128 v[234:237], v198 offset:6144
	ds_read_b128 v[238:241], v199
	ds_read_b128 v[242:245], v199 offset:2048
	ds_read_b128 v[246:249], v199 offset:4096
	ds_read_b128 v[250:253], v199 offset:6144
	global_load_dwordx4 v[162:165], v196, s[44:45] offset:384
	global_load_dwordx4 v[166:169], v208, s[44:45] offset:384
	global_load_dwordx4 v[170:173], v209, s[44:45] offset:384
	global_load_dwordx4 v[174:177], v210, s[44:45] offset:384
	global_load_dwordx4 v[178:181], v196, s[42:43] offset:384
	global_load_dwordx4 v[182:185], v208, s[42:43] offset:384
	global_load_dwordx4 v[186:189], v209, s[42:43] offset:384
	global_load_dwordx4 v[190:193], v210, s[42:43] offset:384
	s_waitcnt lgkmcnt(3)
	v_mfma_f32_16x16x32_bf16 v[6:9], v[238:241], v[212:215], v[6:9]
	v_mfma_f32_16x16x32_bf16 v[10:13], v[238:241], v[216:219], v[10:13]
	v_mfma_f32_16x16x32_bf16 v[14:17], v[238:241], v[220:223], v[14:17]
	v_mfma_f32_16x16x32_bf16 v[18:21], v[238:241], v[234:237], v[18:21]
	ds_read_b128 v[238:241], v199 offset:8192
	s_waitcnt vmcnt(15)
	ds_write_b128 v201, v[130:133]
	s_waitcnt lgkmcnt(4)
	v_mfma_f32_16x16x32_bf16 v[22:25], v[242:245], v[212:215], v[22:25]
	v_mfma_f32_16x16x32_bf16 v[26:29], v[242:245], v[216:219], v[26:29]
	v_mfma_f32_16x16x32_bf16 v[30:33], v[242:245], v[220:223], v[30:33]
	v_mfma_f32_16x16x32_bf16 v[34:37], v[242:245], v[234:237], v[34:37]
	ds_read_b128 v[242:245], v199 offset:10240
	s_waitcnt vmcnt(14)
	ds_write_b128 v201, v[134:137] offset:8192
	ds_read_b128 v[130:133], v200
	s_waitcnt lgkmcnt(6)
	v_mfma_f32_16x16x32_bf16 v[38:41], v[246:249], v[212:215], v[38:41]
	v_mfma_f32_16x16x32_bf16 v[42:45], v[246:249], v[216:219], v[42:45]
	v_mfma_f32_16x16x32_bf16 v[46:49], v[246:249], v[220:223], v[46:49]
	v_mfma_f32_16x16x32_bf16 v[50:53], v[246:249], v[234:237], v[50:53]
	ds_read_b128 v[246:249], v199 offset:12288
	s_waitcnt vmcnt(13)
	ds_write_b128 v201, v[138:141] offset:16384
	ds_read_b128 v[134:137], v200 offset:2048
	s_waitcnt lgkmcnt(8)
	v_mfma_f32_16x16x32_bf16 v[54:57], v[250:253], v[212:215], v[54:57]
	v_mfma_f32_16x16x32_bf16 v[58:61], v[250:253], v[216:219], v[58:61]
	v_mfma_f32_16x16x32_bf16 v[62:65], v[250:253], v[220:223], v[62:65]
	v_mfma_f32_16x16x32_bf16 v[66:69], v[250:253], v[234:237], v[66:69]
	ds_read_b128 v[250:253], v199 offset:14336
	s_waitcnt vmcnt(12)
	ds_write_b128 v201, v[142:145] offset:24576
	ds_read_b128 v[138:141], v200 offset:4096
	s_waitcnt lgkmcnt(10)
	v_mfma_f32_16x16x32_bf16 v[70:73], v[238:241], v[212:215], v[70:73]
	v_mfma_f32_16x16x32_bf16 v[74:77], v[238:241], v[216:219], v[74:77]
	v_mfma_f32_16x16x32_bf16 v[78:81], v[238:241], v[220:223], v[78:81]
	v_mfma_f32_16x16x32_bf16 v[82:85], v[238:241], v[234:237], v[82:85]
	ds_read_b128 v[238:241], v233
	s_waitcnt vmcnt(11)
	ds_write_b128 v201, v[146:149] offset:32768
	ds_read_b128 v[142:145], v200 offset:6144
	s_waitcnt lgkmcnt(11)
	v_mfma_f32_16x16x32_bf16 v[86:89], v[242:245], v[212:215], v[86:89]
	v_mfma_f32_16x16x32_bf16 v[90:93], v[242:245], v[216:219], v[90:93]
	v_mfma_f32_16x16x32_bf16 v[94:97], v[242:245], v[220:223], v[94:97]
	v_mfma_f32_16x16x32_bf16 v[98:101], v[242:245], v[234:237], v[98:101]
	ds_read_b128 v[242:245], v233 offset:2048
	s_waitcnt vmcnt(10)
; #define GCOMPUTE(AS, BS) GCOMPUTE_KS(AS, BS, 0) GCOMPUTE_KS(AS, BS, 1)
; template <int EPI>
; DI void gemm_phase(const P& p, int l, const u16* __restrict__ A, const u16* __restrict__ Bt, int mpx, char* lds) {
;     ...
;   for (int kk = 1; kk < 15; kk += 2) {
;     __syncthreads();
;     GSTORE(As0, Bs0)
;     GLOAD(Ag, Bg, (kk + 2) * 64)
;     __builtin_amdgcn_sched_barrier(0);
;     GCOMPUTE(As1, Bs1)
;     __builtin_amdgcn_sched_barrier(0);
;     __syncthreads();
;     GSTORE(As1, Bs1)
;     {
;       const bool in_tile = kk + 3 < 16;
;       const u16* pa = in_tile ? Ag : Agn;
;       const u16* pb = in_tile ? Bg : Bgn;
;       const int k0 = in_tile ? (kk + 3) * 64 : 0;
;       GLOAD(pa, pb, k0)
;     }
;     __builtin_amdgcn_sched_barrier(0);
;     GCOMPUTE(As0, Bs0)
	ds_write_b128 v201, v[150:153] offset:40960
	s_waitcnt lgkmcnt(10)
	v_mfma_f32_16x16x32_bf16 v[102:105], v[246:249], v[212:215], v[102:105]
	v_mfma_f32_16x16x32_bf16 v[106:109], v[246:249], v[216:219], v[106:109]
	v_mfma_f32_16x16x32_bf16 v[110:113], v[246:249], v[220:223], v[110:113]
	v_mfma_f32_16x16x32_bf16 v[114:117], v[246:249], v[234:237], v[114:117]
	ds_read_b128 v[246:249], v233 offset:4096
	s_waitcnt vmcnt(9)
	ds_write_b128 v201, v[154:157] offset:49152
	s_waitcnt lgkmcnt(9)
	v_mfma_f32_16x16x32_bf16 v[118:121], v[250:253], v[212:215], v[118:121]
	v_mfma_f32_16x16x32_bf16 v[122:125], v[250:253], v[216:219], v[122:125]
	v_mfma_f32_16x16x32_bf16 v[126:129], v[250:253], v[220:223], v[126:129]
	v_mfma_f32_16x16x32_bf16 v[2:5], v[250:253], v[234:237], v[2:5]
	ds_read_b128 v[250:253], v233 offset:6144
	s_waitcnt vmcnt(8)
	ds_write_b128 v201, v[158:161] offset:57344
	s_waitcnt lgkmcnt(6)
	v_mfma_f32_16x16x32_bf16 v[6:9], v[238:241], v[130:133], v[6:9]
	v_mfma_f32_16x16x32_bf16 v[10:13], v[238:241], v[134:137], v[10:13]
	v_mfma_f32_16x16x32_bf16 v[14:17], v[238:241], v[138:141], v[14:17]
	v_mfma_f32_16x16x32_bf16 v[18:21], v[238:241], v[142:145], v[18:21]
	ds_read_b128 v[238:241], v233 offset:8192
	s_waitcnt lgkmcnt(6)
	v_mfma_f32_16x16x32_bf16 v[22:25], v[242:245], v[130:133], v[22:25]
	v_mfma_f32_16x16x32_bf16 v[26:29], v[242:245], v[134:137], v[26:29]
	v_mfma_f32_16x16x32_bf16 v[30:33], v[242:245], v[138:141], v[30:33]
	v_mfma_f32_16x16x32_bf16 v[34:37], v[242:245], v[142:145], v[34:37]
	ds_read_b128 v[242:245], v233 offset:10240
	s_waitcnt lgkmcnt(5)
	v_mfma_f32_16x16x32_bf16 v[38:41], v[246:249], v[130:133], v[38:41]
	v_mfma_f32_16x16x32_bf16 v[42:45], v[246:249], v[134:137], v[42:45]
	v_mfma_f32_16x16x32_bf16 v[46:49], v[246:249], v[138:141], v[46:49]
	v_mfma_f32_16x16x32_bf16 v[50:53], v[246:249], v[142:145], v[50:53]
	ds_read_b128 v[246:249], v233 offset:12288
	s_waitcnt lgkmcnt(4)
	v_mfma_f32_16x16x32_bf16 v[54:57], v[250:253], v[130:133], v[54:57]
	v_mfma_f32_16x16x32_bf16 v[58:61], v[250:253], v[134:137], v[58:61]
	v_mfma_f32_16x16x32_bf16 v[62:65], v[250:253], v[138:141], v[62:65]
	v_mfma_f32_16x16x32_bf16 v[66:69], v[250:253], v[142:145], v[66:69]
	ds_read_b128 v[250:253], v233 offset:14336
	s_waitcnt lgkmcnt(3)
	v_mfma_f32_16x16x32_bf16 v[70:73], v[238:241], v[130:133], v[70:73]
	v_mfma_f32_16x16x32_bf16 v[74:77], v[238:241], v[134:137], v[74:77]
	v_mfma_f32_16x16x32_bf16 v[78:81], v[238:241], v[138:141], v[78:81]
	v_mfma_f32_16x16x32_bf16 v[82:85], v[238:241], v[142:145], v[82:85]
	s_waitcnt lgkmcnt(2)
	v_mfma_f32_16x16x32_bf16 v[86:89], v[242:245], v[130:133], v[86:89]
	v_mfma_f32_16x16x32_bf16 v[90:93], v[242:245], v[134:137], v[90:93]
	v_mfma_f32_16x16x32_bf16 v[94:97], v[242:245], v[138:141], v[94:97]
	v_mfma_f32_16x16x32_bf16 v[98:101], v[242:245], v[142:145], v[98:101]
	s_waitcnt lgkmcnt(1)
	v_mfma_f32_16x16x32_bf16 v[102:105], v[246:249], v[130:133], v[102:105]
	v_mfma_f32_16x16x32_bf16 v[106:109], v[246:249], v[134:137], v[106:109]
	v_mfma_f32_16x16x32_bf16 v[110:113], v[246:249], v[138:141], v[110:113]
	v_mfma_f32_16x16x32_bf16 v[114:117], v[246:249], v[142:145], v[114:117]
	s_waitcnt lgkmcnt(0)
	v_mfma_f32_16x16x32_bf16 v[118:121], v[250:253], v[130:133], v[118:121]
	v_mfma_f32_16x16x32_bf16 v[122:125], v[250:253], v[134:137], v[122:125]
	v_mfma_f32_16x16x32_bf16 v[126:129], v[250:253], v[138:141], v[126:129]
	v_mfma_f32_16x16x32_bf16 v[2:5], v[250:253], v[142:145], v[2:5]
	s_waitcnt lgkmcnt(0)
	s_cmp_lt_u32 s49, 13
	s_cselect_b64 s[62:63], -1, 0
	s_and_b64 s[62:63], s[62:63], exec
	s_cselect_b32 s2, s47, 0
	s_cselect_b32 s57, s41, s59
	s_cselect_b32 s64, s40, s58
	s_cselect_b32 s67, s1, s61
	s_cselect_b32 s68, s0, s60
	s_lshl_b64 s[62:63], s[2:3], 1
	s_add_u32 s64, s64, s62
	s_addc_u32 s65, s57, s63
	s_add_u32 s62, s68, s62
	s_addc_u32 s63, s67, s63
	s_barrier
	ds_read_b128 v[212:215], v204 offset:32768
	ds_read_b128 v[216:219], v204 offset:34816
	ds_read_b128 v[220:223], v204 offset:36864
	ds_read_b128 v[234:237], v204 offset:38912
	ds_read_b128 v[238:241], v205
	ds_read_b128 v[242:245], v205 offset:2048
	ds_read_b128 v[246:249], v205 offset:4096
	ds_read_b128 v[250:253], v205 offset:6144
	global_load_dwordx4 v[130:133], v196, s[64:65]
	global_load_dwordx4 v[134:137], v208, s[64:65]
	global_load_dwordx4 v[138:141], v209, s[64:65]
	global_load_dwordx4 v[142:145], v210, s[64:65]
	global_load_dwordx4 v[146:149], v196, s[62:63]
	global_load_dwordx4 v[150:153], v208, s[62:63]
	global_load_dwordx4 v[154:157], v209, s[62:63]
	global_load_dwordx4 v[158:161], v210, s[62:63]
	s_waitcnt lgkmcnt(3)
	v_mfma_f32_16x16x32_bf16 v[6:9], v[238:241], v[212:215], v[6:9]
	v_mfma_f32_16x16x32_bf16 v[10:13], v[238:241], v[216:219], v[10:13]
	v_mfma_f32_16x16x32_bf16 v[14:17], v[238:241], v[220:223], v[14:17]
	v_mfma_f32_16x16x32_bf16 v[18:21], v[238:241], v[234:237], v[18:21]
	ds_read_b128 v[238:241], v205 offset:8192
	s_waitcnt vmcnt(15)
	ds_write_b128 v202, v[162:165]
	s_waitcnt lgkmcnt(4)
	v_mfma_f32_16x16x32_bf16 v[22:25], v[242:245], v[212:215], v[22:25]
	v_mfma_f32_16x16x32_bf16 v[26:29], v[242:245], v[216:219], v[26:29]
	v_mfma_f32_16x16x32_bf16 v[30:33], v[242:245], v[220:223], v[30:33]
	v_mfma_f32_16x16x32_bf16 v[34:37], v[242:245], v[234:237], v[34:37]
	ds_read_b128 v[242:245], v205 offset:10240
	s_waitcnt vmcnt(14)
	ds_write_b128 v227, v[166:169]
	ds_read_b128 v[162:165], v206 offset:32768
	s_waitcnt lgkmcnt(6)
	v_mfma_f32_16x16x32_bf16 v[38:41], v[246:249], v[212:215], v[38:41]
	v_mfma_f32_16x16x32_bf16 v[42:45], v[246:249], v[216:219], v[42:45]
	v_mfma_f32_16x16x32_bf16 v[46:49], v[246:249], v[220:223], v[46:49]
	v_mfma_f32_16x16x32_bf16 v[50:53], v[246:249], v[234:237], v[50:53]
	ds_read_b128 v[246:249], v205 offset:12288
	s_waitcnt vmcnt(13)
; #define GCOMPUTE(AS, BS) GCOMPUTE_KS(AS, BS, 0) GCOMPUTE_KS(AS, BS, 1)
; template <int EPI>
; DI void gemm_phase(const P& p, int l, const u16* __restrict__ A, const u16* __restrict__ Bt, int mpx, char* lds) {
;     ...
;   for (int kk = 1; kk < 15; kk += 2) {
;     __syncthreads();
;     GSTORE(As0, Bs0)
;     GLOAD(Ag, Bg, (kk + 2) * 64)
;     __builtin_amdgcn_sched_barrier(0);
;     GCOMPUTE(As1, Bs1)
;     __builtin_amdgcn_sched_barrier(0);
;     __syncthreads();
;     GSTORE(As1, Bs1)
;     {
;       const bool in_tile = kk + 3 < 16;
;       const u16* pa = in_tile ? Ag : Agn;
;       const u16* pb = in_tile ? Bg : Bgn;
;       const int k0 = in_tile ? (kk + 3) * 64 : 0;
;       GLOAD(pa, pb, k0)
;     }
;     __builtin_amdgcn_sched_barrier(0);
;     GCOMPUTE(As0, Bs0)
;     __builtin_amdgcn_sched_barrier(0);
;   }
	ds_write_b128 v228, v[170:173]
	ds_read_b128 v[166:169], v206 offset:34816
	s_waitcnt lgkmcnt(8)
	v_mfma_f32_16x16x32_bf16 v[54:57], v[250:253], v[212:215], v[54:57]
	v_mfma_f32_16x16x32_bf16 v[58:61], v[250:253], v[216:219], v[58:61]
	v_mfma_f32_16x16x32_bf16 v[62:65], v[250:253], v[220:223], v[62:65]
	v_mfma_f32_16x16x32_bf16 v[66:69], v[250:253], v[234:237], v[66:69]
	ds_read_b128 v[250:253], v205 offset:14336
	s_waitcnt vmcnt(12)
	ds_write_b128 v229, v[174:177]
	ds_read_b128 v[170:173], v206 offset:36864
	s_waitcnt lgkmcnt(10)
	v_mfma_f32_16x16x32_bf16 v[70:73], v[238:241], v[212:215], v[70:73]
	v_mfma_f32_16x16x32_bf16 v[74:77], v[238:241], v[216:219], v[74:77]
	v_mfma_f32_16x16x32_bf16 v[78:81], v[238:241], v[220:223], v[78:81]
	v_mfma_f32_16x16x32_bf16 v[82:85], v[238:241], v[234:237], v[82:85]
	ds_read_b128 v[238:241], v207
	s_waitcnt vmcnt(11)
	ds_write_b128 v203, v[178:181]
	ds_read_b128 v[174:177], v206 offset:38912
	s_waitcnt lgkmcnt(11)
	v_mfma_f32_16x16x32_bf16 v[86:89], v[242:245], v[212:215], v[86:89]
	v_mfma_f32_16x16x32_bf16 v[90:93], v[242:245], v[216:219], v[90:93]
	v_mfma_f32_16x16x32_bf16 v[94:97], v[242:245], v[220:223], v[94:97]
	v_mfma_f32_16x16x32_bf16 v[98:101], v[242:245], v[234:237], v[98:101]
	ds_read_b128 v[242:245], v207 offset:2048
	s_waitcnt vmcnt(10)
	ds_write_b128 v230, v[182:185]
	s_waitcnt lgkmcnt(10)
	v_mfma_f32_16x16x32_bf16 v[102:105], v[246:249], v[212:215], v[102:105]
	v_mfma_f32_16x16x32_bf16 v[106:109], v[246:249], v[216:219], v[106:109]
	v_mfma_f32_16x16x32_bf16 v[110:113], v[246:249], v[220:223], v[110:113]
	v_mfma_f32_16x16x32_bf16 v[114:117], v[246:249], v[234:237], v[114:117]
	ds_read_b128 v[246:249], v207 offset:4096
	s_waitcnt vmcnt(9)
	ds_write_b128 v231, v[186:189]
	s_waitcnt lgkmcnt(9)
	v_mfma_f32_16x16x32_bf16 v[118:121], v[250:253], v[212:215], v[118:121]
	v_mfma_f32_16x16x32_bf16 v[122:125], v[250:253], v[216:219], v[122:125]
	v_mfma_f32_16x16x32_bf16 v[126:129], v[250:253], v[220:223], v[126:129]
	v_mfma_f32_16x16x32_bf16 v[2:5], v[250:253], v[234:237], v[2:5]
	ds_read_b128 v[250:253], v207 offset:6144
	s_waitcnt vmcnt(8)
	ds_write_b128 v232, v[190:193]
	s_waitcnt lgkmcnt(6)
	v_mfma_f32_16x16x32_bf16 v[6:9], v[238:241], v[162:165], v[6:9]
	v_mfma_f32_16x16x32_bf16 v[10:13], v[238:241], v[166:169], v[10:13]
	v_mfma_f32_16x16x32_bf16 v[14:17], v[238:241], v[170:173], v[14:17]
	v_mfma_f32_16x16x32_bf16 v[18:21], v[238:241], v[174:177], v[18:21]
	ds_read_b128 v[238:241], v207 offset:8192
	s_waitcnt lgkmcnt(6)
	v_mfma_f32_16x16x32_bf16 v[22:25], v[242:245], v[162:165], v[22:25]
	v_mfma_f32_16x16x32_bf16 v[26:29], v[242:245], v[166:169], v[26:29]
	v_mfma_f32_16x16x32_bf16 v[30:33], v[242:245], v[170:173], v[30:33]
	v_mfma_f32_16x16x32_bf16 v[34:37], v[242:245], v[174:177], v[34:37]
	ds_read_b128 v[242:245], v207 offset:10240
	s_waitcnt lgkmcnt(5)
	v_mfma_f32_16x16x32_bf16 v[38:41], v[246:249], v[162:165], v[38:41]
	v_mfma_f32_16x16x32_bf16 v[42:45], v[246:249], v[166:169], v[42:45]
	v_mfma_f32_16x16x32_bf16 v[46:49], v[246:249], v[170:173], v[46:49]
	v_mfma_f32_16x16x32_bf16 v[50:53], v[246:249], v[174:177], v[50:53]
	ds_read_b128 v[246:249], v207 offset:12288
	s_waitcnt lgkmcnt(4)
	v_mfma_f32_16x16x32_bf16 v[54:57], v[250:253], v[162:165], v[54:57]
	v_mfma_f32_16x16x32_bf16 v[58:61], v[250:253], v[166:169], v[58:61]
	v_mfma_f32_16x16x32_bf16 v[62:65], v[250:253], v[170:173], v[62:65]
	v_mfma_f32_16x16x32_bf16 v[66:69], v[250:253], v[174:177], v[66:69]
	ds_read_b128 v[250:253], v207 offset:14336
	s_waitcnt lgkmcnt(3)
	v_mfma_f32_16x16x32_bf16 v[70:73], v[238:241], v[162:165], v[70:73]
	v_mfma_f32_16x16x32_bf16 v[74:77], v[238:241], v[166:169], v[74:77]
	v_mfma_f32_16x16x32_bf16 v[78:81], v[238:241], v[170:173], v[78:81]
	v_mfma_f32_16x16x32_bf16 v[82:85], v[238:241], v[174:177], v[82:85]
	s_waitcnt lgkmcnt(2)
	v_mfma_f32_16x16x32_bf16 v[86:89], v[242:245], v[162:165], v[86:89]
	v_mfma_f32_16x16x32_bf16 v[90:93], v[242:245], v[166:169], v[90:93]
	v_mfma_f32_16x16x32_bf16 v[94:97], v[242:245], v[170:173], v[94:97]
	v_mfma_f32_16x16x32_bf16 v[98:101], v[242:245], v[174:177], v[98:101]
	s_waitcnt lgkmcnt(1)
	v_mfma_f32_16x16x32_bf16 v[102:105], v[246:249], v[162:165], v[102:105]
	v_mfma_f32_16x16x32_bf16 v[106:109], v[246:249], v[166:169], v[106:109]
	v_mfma_f32_16x16x32_bf16 v[110:113], v[246:249], v[170:173], v[110:113]
	v_mfma_f32_16x16x32_bf16 v[114:117], v[246:249], v[174:177], v[114:117]
	s_waitcnt lgkmcnt(0)
	v_mfma_f32_16x16x32_bf16 v[118:121], v[250:253], v[162:165], v[118:121]
	v_mfma_f32_16x16x32_bf16 v[122:125], v[250:253], v[166:169], v[122:125]
	v_mfma_f32_16x16x32_bf16 v[126:129], v[250:253], v[170:173], v[126:129]
	v_mfma_f32_16x16x32_bf16 v[2:5], v[250:253], v[174:177], v[2:5]
	s_waitcnt lgkmcnt(0)
	s_addk_i32 s47, 0x80
	s_add_u32 s44, s44, 0x100
	s_addc_u32 s45, s45, 0
	s_add_u32 s42, s42, 0x100
	s_addc_u32 s43, s43, 0
	s_cmp_gt_u32 s49, 12
	s_mov_b32 s49, s48
	s_cbranch_scc0 .LBB0_82
	s_barrier
; #define GCOMPUTE(AS, BS) GCOMPUTE_KS(AS, BS, 0) GCOMPUTE_KS(AS, BS, 1)
; template <int EPI>
; DI void gemm_phase(const P& p, int l, const u16* __restrict__ A, const u16* __restrict__ Bt, int mpx, char* lds) {
;     ...
;   __syncthreads();
;   __builtin_amdgcn_sched_barrier(0);
;   GCOMPUTE(As1, Bs1)
;   __builtin_amdgcn_sched_barrier(0);
	ds_read_b128 v[162:165], v199
	ds_read_b128 v[166:169], v198
	ds_read_b128 v[170:173], v198 offset:2048
	ds_read_b128 v[174:177], v198 offset:4096
	ds_read_b128 v[178:181], v198 offset:6144
	s_waitcnt lgkmcnt(3)
	v_mfma_f32_16x16x32_bf16 v[6:9], v[162:165], v[166:169], v[6:9]
	s_waitcnt lgkmcnt(2)
	v_mfma_f32_16x16x32_bf16 v[10:13], v[162:165], v[170:173], v[10:13]
	s_waitcnt lgkmcnt(1)
	v_mfma_f32_16x16x32_bf16 v[14:17], v[162:165], v[174:177], v[14:17]
	s_waitcnt lgkmcnt(0)
	v_mfma_f32_16x16x32_bf16 v[18:21], v[162:165], v[178:181], v[18:21]
	ds_read_b128 v[162:165], v199 offset:2048
	s_waitcnt lgkmcnt(0)
	v_mfma_f32_16x16x32_bf16 v[22:25], v[162:165], v[166:169], v[22:25]
	v_mfma_f32_16x16x32_bf16 v[26:29], v[162:165], v[170:173], v[26:29]
	v_mfma_f32_16x16x32_bf16 v[30:33], v[162:165], v[174:177], v[30:33]
	v_mfma_f32_16x16x32_bf16 v[34:37], v[162:165], v[178:181], v[34:37]
	ds_read_b128 v[162:165], v199 offset:4096
	s_waitcnt lgkmcnt(0)
	v_mfma_f32_16x16x32_bf16 v[38:41], v[162:165], v[166:169], v[38:41]
	v_mfma_f32_16x16x32_bf16 v[42:45], v[162:165], v[170:173], v[42:45]
	v_mfma_f32_16x16x32_bf16 v[46:49], v[162:165], v[174:177], v[46:49]
	v_mfma_f32_16x16x32_bf16 v[50:53], v[162:165], v[178:181], v[50:53]
	ds_read_b128 v[162:165], v199 offset:6144
	s_waitcnt lgkmcnt(0)
	v_mfma_f32_16x16x32_bf16 v[54:57], v[162:165], v[166:169], v[54:57]
	v_mfma_f32_16x16x32_bf16 v[58:61], v[162:165], v[170:173], v[58:61]
	v_mfma_f32_16x16x32_bf16 v[62:65], v[162:165], v[174:177], v[62:65]
	v_mfma_f32_16x16x32_bf16 v[66:69], v[162:165], v[178:181], v[66:69]
	ds_read_b128 v[162:165], v199 offset:8192
	s_waitcnt lgkmcnt(0)
	v_mfma_f32_16x16x32_bf16 v[182:185], v[162:165], v[166:169], v[70:73]
	s_nop 2
	ds_read_b128 v[70:73], v199 offset:10240
	v_mfma_f32_16x16x32_bf16 v[186:189], v[162:165], v[170:173], v[74:77]
	s_nop 2
	ds_read_b128 v[74:77], v233
	s_waitcnt lgkmcnt(1)
	v_mfma_f32_16x16x32_bf16 v[212:215], v[70:73], v[166:169], v[86:89]
	v_mfma_f32_16x16x32_bf16 v[216:219], v[70:73], v[170:173], v[90:93]
	v_mfma_f32_16x16x32_bf16 v[220:223], v[70:73], v[174:177], v[94:97]
	v_mfma_f32_16x16x32_bf16 v[234:237], v[70:73], v[178:181], v[98:101]
	ds_read_b128 v[70:73], v199 offset:12288
	s_waitcnt lgkmcnt(0)
	v_mfma_f32_16x16x32_bf16 v[238:241], v[70:73], v[166:169], v[102:105]
	v_mfma_f32_16x16x32_bf16 v[242:245], v[70:73], v[170:173], v[106:109]
	v_mfma_f32_16x16x32_bf16 v[246:249], v[70:73], v[174:177], v[110:113]
	v_mfma_f32_16x16x32_bf16 v[250:253], v[70:73], v[178:181], v[114:117]
	ds_read_b128 v[70:73], v199 offset:14336
	v_mfma_f32_16x16x32_bf16 v[190:193], v[162:165], v[174:177], v[78:81]
	v_mfma_f32_16x16x32_bf16 v[162:165], v[162:165], v[178:181], v[82:85]
	s_waitcnt lgkmcnt(0)
	v_mfma_f32_16x16x32_bf16 v[178:181], v[70:73], v[178:181], v[2:5]
	s_nop 2
	ds_read_b128 v[2:5], v200
	v_mfma_f32_16x16x32_bf16 v[174:177], v[70:73], v[174:177], v[126:129]
	s_waitcnt lgkmcnt(0)
	v_mfma_f32_16x16x32_bf16 v[126:129], v[74:77], v[2:5], v[6:9]
	s_nop 2
	ds_read_b128 v[6:9], v200 offset:2048
	v_mfma_f32_16x16x32_bf16 v[170:173], v[70:73], v[170:173], v[122:125]
	s_waitcnt lgkmcnt(0)
	v_mfma_f32_16x16x32_bf16 v[122:125], v[74:77], v[6:9], v[10:13]
	s_nop 2
	ds_read_b128 v[10:13], v200 offset:4096
	v_mfma_f32_16x16x32_bf16 v[166:169], v[70:73], v[166:169], v[118:121]
	s_waitcnt lgkmcnt(0)
	v_mfma_f32_16x16x32_bf16 v[118:121], v[74:77], v[10:13], v[14:17]
	s_nop 2
	ds_read_b128 v[14:17], v200 offset:6144
	s_waitcnt lgkmcnt(0)
	v_mfma_f32_16x16x32_bf16 v[114:117], v[74:77], v[14:17], v[18:21]
	s_nop 2
	ds_read_b128 v[18:21], v233 offset:2048
	s_waitcnt lgkmcnt(0)
	v_mfma_f32_16x16x32_bf16 v[110:113], v[18:21], v[2:5], v[22:25]
	v_mfma_f32_16x16x32_bf16 v[106:109], v[18:21], v[6:9], v[26:29]
	v_mfma_f32_16x16x32_bf16 v[102:105], v[18:21], v[10:13], v[30:33]
	v_mfma_f32_16x16x32_bf16 v[98:101], v[18:21], v[14:17], v[34:37]
	ds_read_b128 v[18:21], v233 offset:4096
	s_waitcnt lgkmcnt(0)
	v_mfma_f32_16x16x32_bf16 v[94:97], v[18:21], v[2:5], v[38:41]
	v_mfma_f32_16x16x32_bf16 v[90:93], v[18:21], v[6:9], v[42:45]
	v_mfma_f32_16x16x32_bf16 v[86:89], v[18:21], v[10:13], v[46:49]
	v_mfma_f32_16x16x32_bf16 v[82:85], v[18:21], v[14:17], v[50:53]
	ds_read_b128 v[18:21], v233 offset:6144
	s_waitcnt lgkmcnt(0)
	v_mfma_f32_16x16x32_bf16 v[78:81], v[18:21], v[2:5], v[54:57]
	v_mfma_f32_16x16x32_bf16 v[74:77], v[18:21], v[6:9], v[58:61]
	v_mfma_f32_16x16x32_bf16 v[70:73], v[18:21], v[10:13], v[62:65]
	v_mfma_f32_16x16x32_bf16 v[66:69], v[18:21], v[14:17], v[66:69]
	ds_read_b128 v[18:21], v233 offset:8192
	s_waitcnt lgkmcnt(0)
	v_mfma_f32_16x16x32_bf16 v[62:65], v[18:21], v[2:5], v[182:185]
	s_nop 2
	ds_read_b128 v[182:185], v233 offset:14336
	v_mfma_f32_16x16x32_bf16 v[58:61], v[18:21], v[6:9], v[186:189]
	v_mfma_f32_16x16x32_bf16 v[54:57], v[18:21], v[10:13], v[190:193]
	v_mfma_f32_16x16x32_bf16 v[50:53], v[18:21], v[14:17], v[162:165]
	ds_read_b128 v[18:21], v233 offset:10240
	s_waitcnt lgkmcnt(0)
	v_mfma_f32_16x16x32_bf16 v[46:49], v[18:21], v[2:5], v[212:215]
	v_mfma_f32_16x16x32_bf16 v[42:45], v[18:21], v[6:9], v[216:219]
	v_mfma_f32_16x16x32_bf16 v[38:41], v[18:21], v[10:13], v[220:223]
	v_mfma_f32_16x16x32_bf16 v[34:37], v[18:21], v[14:17], v[234:237]
	ds_read_b128 v[18:21], v233 offset:12288
	s_waitcnt lgkmcnt(0)
	v_mfma_f32_16x16x32_bf16 v[30:33], v[18:21], v[2:5], v[238:241]
	v_mfma_f32_16x16x32_bf16 v[26:29], v[18:21], v[6:9], v[242:245]
	v_mfma_f32_16x16x32_bf16 v[22:25], v[18:21], v[10:13], v[246:249]
	v_mfma_f32_16x16x32_bf16 v[18:21], v[18:21], v[14:17], v[250:253]
	v_mfma_f32_16x16x32_bf16 v[166:169], v[182:185], v[2:5], v[166:169]
	v_mfma_f32_16x16x32_bf16 v[162:165], v[182:185], v[6:9], v[170:173]
	v_mfma_f32_16x16x32_bf16 v[2:5], v[182:185], v[10:13], v[174:177]
	v_mfma_f32_16x16x32_bf16 v[6:9], v[182:185], v[14:17], v[178:181]
	s_barrier
; template <int EPI>
; DI void gemm_phase(const P& p, int l, const u16* __restrict__ A, const u16* __restrict__ Bt, int mpx, char* lds) {
;     ...
;   __syncthreads();
;   GSTORE(As0, Bs0)
;     ...
;     const int cb = n0 + wn * 64;
;     const bool isctx = m0 >= MLAT;
;     const int b = isctx ? ((m0 - MLAT) >> 8) : (m0 >> 11);
;     const int tokw = (isctx ? 2048 + ((m0 - MLAT) & 255) : (m0 & 2047)) + wm * 128;
;     u16* Tl = (u16*)(lds + 65536) + w * (64 * 72);
;     int kind = 0;
;     int tr = 0;
;     bool donorm = false;
;     if (cb >= 2816) { kind = 2; tr = 1; }
;     else if (cb < 256) tr = 1;
;     else if (cb < 512) tr = 0;
;     else if (cb < 1024) tr = 2;
;     else if (cb < 1408) { tr = 3; donorm = true; }
;     else if (cb < 1536) kind = 1;
;     else if (cb < 2048) tr = isctx ? 0 : 4;
;     else if (cb < 2304) kind = 1;
;     else if (cb < 2688) tr = isctx ? 0 : 3;
;     else kind = 1;
	s_waitcnt vmcnt(7)
	ds_write_b128 v201, v[130:133]
	s_waitcnt vmcnt(5)
	ds_write_b128 v201, v[134:137] offset:8192
	s_waitcnt vmcnt(4)
	ds_write_b128 v201, v[138:141] offset:16384
	s_waitcnt vmcnt(3)
	ds_write_b128 v201, v[142:145] offset:24576
	ds_write_b128 v201, v[146:149] offset:32768
	s_waitcnt vmcnt(2)
	ds_write_b128 v201, v[150:153] offset:40960
	s_waitcnt vmcnt(1)
	ds_write_b128 v201, v[154:157] offset:49152
	s_waitcnt vmcnt(0)
	ds_write_b128 v201, v[158:161] offset:57344
	v_mov_b32_e32 v148, v195
	s_movk_i32 s0, 0xf5ff
	v_and_b32_e32 v0, 0xc0, v148
	v_add_u32_e32 v140, s46, v0
	v_mov_b32_e32 v0, 0x8000
	v_sub_co_u32_e32 v137, vcc, s66, v0
	v_add_u32_e32 v0, 0xfffff500, v140
	v_cmp_lt_u32_e64 s[40:41], s0, v0
	v_mov_b32_e32 v147, 1
	s_mov_b64 s[64:65], 0
	s_mov_b64 s[0:1], 0
	s_mov_b64 s[42:43], exec
	s_and_b64 s[40:41], s[42:43], s[40:41]
	v_mov_b32_e32 v236, 0x358637bd
	s_mov_b64 exec, s[40:41]
	s_cbranch_execz .LBB0_97
	s_movk_i32 s0, 0x1ff
	v_cmp_lt_u32_e64 s[40:41], s0, v140
	v_mov_b32_e32 v147, 0
	s_mov_b64 s[46:47], 0
	s_mov_b64 s[44:45], 0
	s_and_saveexec_b64 s[0:1], s[40:41]
	s_cbranch_execz .LBB0_96
	s_movk_i32 s2, 0x3ff
	v_cmp_lt_u32_e64 s[40:41], s2, v140
	v_mov_b32_e32 v147, 2
	s_mov_b64 s[62:63], 0
	s_and_saveexec_b64 s[44:45], s[40:41]
	s_cbranch_execz .LBB0_95
	s_movk_i32 s2, 0x57f
	v_cmp_lt_u32_e64 s[40:41], s2, v140
	s_mov_b64 s[48:49], 0
	v_mov_b32_e32 v147, 3
	s_mov_b64 s[62:63], -1
	s_and_saveexec_b64 s[46:47], s[40:41]
	s_cbranch_execz .LBB0_94
	s_movk_i32 s2, 0x5ff
	v_cmp_lt_u32_e64 s[40:41], s2, v140
	s_mov_b64 s[64:65], -1
	v_mov_b32_e32 v147, 0
	s_and_saveexec_b64 s[48:49], s[40:41]
	s_cbranch_execz .LBB0_93
	s_movk_i32 s2, 0x7ff
	v_cmp_lt_u32_e64 s[40:41], s2, v140
	s_and_saveexec_b64 s[64:65], s[40:41]
	s_xor_b64 s[40:41], exec, s[64:65]
	s_and_b64 s[62:63], vcc, exec
	s_cselect_b32 s2, 3, 0
	v_add_u32_e32 v0, 0xfffff580, v140
	v_mov_b32_e32 v10, s2
	s_movk_i32 s2, 0xfe80
	v_cmp_gt_u32_e64 s[62:63], s2, v0
	s_nop 1
	v_cndmask_b32_e64 v147, v10, 0, s[62:63]
	s_andn2_saveexec_b64 s[40:41], s[40:41]
	s_and_b64 s[64:65], vcc, exec
	s_cselect_b32 s2, 4, 0
	v_mov_b32_e32 v147, s2
	s_andn2_b64 s[62:63], s[62:63], exec
	s_or_b64 exec, exec, s[40:41]
	s_orn2_b64 s[64:65], s[62:63], exec
